# attention deferred-rescale threshold 2^6 -> 2^16 (same math, fewer reference moves; p <= 65536 stays far inside bf16/f32 range)
# speedup vs baseline: 1.0081x; 1.0081x over previous
; #define LAS __attribute__((address_space(3)))
; DI float bflo(unsigned u) { return __uint_as_float(u << 16); }
; DI float bfhi(unsigned u) { return __uint_as_float(u & 0xffff0000u); }
; DI void attn_unit(int b, int h, int qb, const bf16* Qb, const bf16* Kb, const bf16* Vt, const int* positions, bf16* O, LAS unsigned char* lds, int tid) {
;     const int wave = __builtin_amdgcn_readfirstlane(tid >> 6), lane = tid & 63, r32 = lane & 31, hi = lane >> 5;
;     const int rowbase = b * T, q0 = qb * 256, qrow = q0 + 32 * wave + r32;
;     const int kkey0 = tid / 12, kc0 = tid % 12, vd = tid >> 3, vc = tid & 7;
;     const bf16* kg0 = Kb + (size_t)(rowbase + kkey0) * 768 + h * 96 + kc0 * 8;
;     const bf16* vg = Vt + (size_t)(h * 64 + vd) * VT_LD + rowbase + vc * 8;
;     const int NT = (q0 + 256) / 64, NTF = q0 / 64;
;     const int kp1 = tid < 256 ? 512 + tid : tid;
;     const int kkey1 = kp1 / 12, kc1 = kp1 % 12;
;     const bf16* kg1 = Kb + (size_t)(rowbase + kkey1) * 768 + h * 96 + kc1 * 8;
;     u32x4 kA0, kA1, vA, kB0, kB1, vB, kC0, kC1, vC;
;     ...
;     AT_ISSUE(A, 0); AT_ISSUE(B, 1); AT_ISSUE(C, 2);
;     bf16x8 qr[6];
;     {
;         const bf16* qp = Qb + (size_t)(rowbase + qrow) * 768 + h * 96 + 8 * hi;
;         float qv[6][8];
; #pragma unroll
;         for (int d0 = 0; d0 < 6; ++d0) { const u32x4 a = *(const u32x4*)(qp + 16 * d0);
;             qv[d0][0] = bflo(a.x); qv[d0][1] = bfhi(a.x); qv[d0][2] = bflo(a.y); qv[d0][3] = bfhi(a.y); qv[d0][4] = bflo(a.z); qv[d0][5] = bfhi(a.z); qv[d0][6] = bflo(a.w); qv[d0][7] = bfhi(a.w); }
;         const int pos = positions[rowbase + qrow];
; #pragma unroll
;         for (int i = 0; i < 8; ++i) { float c, s; rope_cs(pos, 8 * hi + i, c, s); const float x1 = qv[4][i], x2 = qv[5][i]; qv[4][i] = x1 * c - x2 * s; qv[5][i] = x1 * s + x2 * c; }
;         const float C2 = 0.10206207261596575f * 1.4426950408889634f;
; #pragma unroll
; __global__ void __launch_bounds__(512, 2) mk_fwd(Args a) {
;     ...
;         int ticket = 0;
;         if (tid == 0) ticket = (int)xb_add(&barw[XB_QHEAD(xq)], 1u);
;         if (tid == 0) *qslot = ticket;
;         __syncthreads();
;         int q = *qslot;
;         __syncthreads();
;         while (q < per_q) {
;             if (tid == 0) ticket = (int)xb_add(&barw[XB_QHEAD(xq)], 1u);
;             const int bh = NQ == 8 ? xq * 8 + (q & 7) : (q & 63), qb = NQ == 8 ? 15 - (q >> 3) : 15 - (q >> 6);
.LBB0_836:
	s_or_b64 exec, exec, s[2:3]
	s_and_saveexec_b64 s[2:3], s[0:1]
	s_add_i32 s12, 0, 0x24fe0
	v_mov_b32_e32 v0, s12
	ds_write_b32 v0, v200
	s_or_b64 exec, exec, s[2:3]
	v_lshlrev_b32_e32 v254, 2, v197
	global_load_dword v255, v254, s[86:87]
	s_waitcnt vmcnt(0)
	v_add_u32_e32 v254, 0x20000, v254
	ds_write_b32 v254, v255
	s_movk_i32 s12, 0x80
	s_and_b64 s[2:3], s[8:9], exec
	s_cselect_b32 s17, s12, 0x400
	s_add_i32 s24, 0, 0x24fe0
	v_mov_b32_e32 v0, s24
	s_waitcnt vmcnt(0) lgkmcnt(0)
	s_barrier
	ds_read_b32 v0, v0
	s_mov_b32 s13, 0
	s_waitcnt lgkmcnt(0)
	s_barrier
	v_cmp_le_i32_e32 vcc, s17, v0
	v_readfirstlane_b32 s12, v0
	s_cbranch_vccnz .LBB0_871
	s_lshl_b32 s25, s16, 3
	s_and_b64 s[2:3], s[8:9], exec
	s_movk_i32 s2, 0x100
	v_bfe_u32 v3, v197, 5, 1
	v_cmp_gt_u32_e32 vcc, s2, v197
	s_movk_i32 s2, 0x88
	v_mad_u32_u24 v204, v198, s2, 0
	v_mov_b32_e32 v8, 0x3f847ae1
	v_mov_b32_e32 v9, 0x3ff00000
	v_cmp_eq_u32_e64 s[2:3], 0, v3
	v_add_u32_e32 v2, 0x200, v197
	v_mul_u32_u24_e32 v0, 0x1556, v197
	v_cndmask_b32_e64 v165, v8, v9, s[2:3]
	v_mov_b32_e32 v8, 0x47ae147b
	v_cndmask_b32_e64 v164, v8, 0, s[2:3]
	v_mov_b32_e32 v8, 0x3f770893
	v_mov_b32_e32 v9, 0x3fe1feb3
	v_cndmask_b32_e64 v167, v8, v9, s[2:3]
	v_mov_b32_e32 v8, 0x80241edf
	v_mov_b32_e32 v9, 0x3c1c381e
	v_cndmask_b32_e64 v166, v8, v9, s[2:3]
	v_mov_b32_e32 v8, 0x3f69e7c6
	v_mov_b32_e32 v9, 0x3fd43d13
	v_cndmask_b32_e64 v169, v8, v9, s[2:3]
	v_mov_b32_e32 v8, 0xe43390b7
	v_mov_b32_e32 v9, 0x6248490f
	v_cndmask_b32_e64 v168, v8, v9, s[2:3]
	v_mov_b32_e32 v8, 0x3f5d22a4
	v_mov_b32_e32 v9, 0x3fc6c310
	v_cndmask_b32_e64 v171, v8, v9, s[2:3]
	v_mov_b32_e32 v8, 0xfa316fad
	v_mov_b32_e32 v9, 0xe3769f3f
	v_cndmask_b32_e64 v170, v8, v9, s[2:3]
	v_mov_b32_e32 v8, 0x3f50624d
	v_mov_b32_e32 v9, 0x3fb99999
	v_cndmask_b32_e64 v173, v8, v9, s[2:3]
	v_mov_b32_e32 v8, 0xd2f1a9fc
	v_mov_b32_e32 v9, 0x9999999a
	v_cndmask_b32_e32 v2, v197, v2, vcc
	v_cndmask_b32_e64 v172, v8, v9, s[2:3]
	v_mov_b32_e32 v8, 0x3f426d42
	v_mov_b32_e32 v9, 0x3faccab8
	v_lshrrev_b32_e32 v202, 16, v0
	v_mul_u32_u24_e32 v5, 0x1556, v2
	v_cndmask_b32_e64 v175, v8, v9, s[2:3]
	v_mov_b32_e32 v8, 0xcce9b24c
	v_mov_b32_e32 v9, 0x602d2697
	v_and_b32_e32 v201, 31, v197
	v_mul_lo_u16_e32 v0, 12, v202
	v_lshrrev_b32_e32 v203, 16, v5
	s_movk_i32 s14, 0xd0
	v_cndmask_b32_e64 v174, v8, v9, s[2:3]
	v_mov_b32_e32 v8, 0x3f34b96b
	v_mov_b32_e32 v9, 0x3fa030dc
	v_sub_u16_e32 v4, v197, v0
	v_mov_b32_e32 v1, 0
	v_mul_lo_u16_e32 v5, 12, v203
	v_mad_u32_u24 v6, v202, s14, 0
	v_mad_u32_u24 v7, v203, s14, 0
	v_cndmask_b32_e64 v177, v8, v9, s[2:3]
	v_mov_b32_e32 v8, 0xe9c2da2c
	v_mov_b32_e32 v9, 0x4ea03a73
	v_mad_u32_u24 v206, v201, s14, 0
	v_readlane_b32 s14, v253, 45
	v_lshlrev_b32_e32 v0, 3, v4
	v_sub_u16_e32 v5, v2, v5
	v_lshlrev_b32_e32 v160, 4, v3
	v_mov_b32_e32 v161, v1
	v_cndmask_b32_e64 v176, v8, v9, s[2:3]
	v_mov_b32_e32 v8, 0x3f274eea
	v_mov_b32_e32 v9, 0x3f9235a7
	v_readlane_b32 s15, v253, 46
	v_readlane_b32 s20, v253, 51
	v_lshlrev_b32_e32 v2, 3, v5
	v_lshlrev_b32_e32 v4, 4, v4
	v_lshlrev_b32_e32 v5, 4, v5
	v_cndmask_b32_e64 v179, v8, v9, s[2:3]
	v_mov_b32_e32 v8, 0x61c12624
	v_mov_b32_e32 v9, 0x1c5ee5cc
	v_lshl_add_u64 v[180:181], s[14:15], 0, v[160:161]
	v_lshlrev_b32_e32 v182, 1, v0
	s_movk_i32 s18, 0x3400
	s_mov_b32 s14, 0x6dc9c883
	v_readlane_b32 s21, v253, 52
	v_mbcnt_lo_u32_b32 v0, -1, 0
	s_cselect_b32 s26, 3, 6
	v_lshl_add_u64 v[162:163], s[84:85], 0, v[160:161]
	v_cndmask_b32_e64 v178, v8, v9, s[2:3]
	v_lshl_add_u32 v205, v3, 3, 0
	v_lshlrev_b32_e32 v207, 2, v3
	v_mul_u32_u24_e32 v208, 0x88, v201
	s_movk_i32 s27, 0x600
	v_mov_b32_e32 v183, v1
	v_lshlrev_b32_e32 v184, 1, v2
	s_mov_b32 s15, 0x3fc45f30
	s_mov_b32 s16, 0x3e16c740
	s_mov_b32 s28, 0x48000
	s_mov_b32 s29, 0x8a00
	s_mov_b32 s30, 0x41800000
	s_mov_b32 s31, 0xe000
	v_mov_b64_e32 v[186:187], s[20:21]
	v_mov_b32_e32 v161, 0x18000
	v_add_u32_e32 v209, v6, v4
	v_add_u32_e32 v210, v7, v5
	v_add3_u32 v211, v204, v199, s18
	v_mov_b32_e32 v212, 0xff800000
	v_mbcnt_hi_u32_b32 v213, -1, v0
	s_branch .LBB0_841
